# prep phase parameter-load hoist distance 8 -> 12 steps
# speedup vs baseline: 1.0147x; 1.0023x over previous
.LBB0_304:
	s_or_b64 exec, exec, s[2:3]
	global_load_dword v236, v[38:39], off
	global_load_dword v237, v[30:31], off offset:1024
	global_load_dword v238, v[30:31], off offset:1280
	global_load_dword v239, v[30:31], off offset:1536
	global_load_dword v240, v[40:41], off
	global_load_dword v241, v[30:31], off offset:2048
	global_load_dword v242, v[78:79], off
	global_load_dword v243, v[30:31], off offset:2304
	global_load_dword v244, v[78:79], off offset:256
	global_load_dword v245, v[30:31], off offset:2560
	global_load_dword v246, v[78:79], off offset:512
	global_load_dword v247, v[42:43], off
	v_lshlrev_b64 v[136:137], 9, v[106:107]
	v_add_f32_e32 v111, v111, v169
	v_fma_f32 v111, v111, 0.5, -v109
	v_readlane_b32 s4, v252, 48
	v_readlane_b32 s12, v252, 56
	v_readlane_b32 s13, v252, 57
	s_mov_b32 s4, 0xf800000
	v_readlane_b32 s10, v252, 54
	v_readlane_b32 s11, v252, 55
	v_readlane_b32 s8, v252, 52
	v_readlane_b32 s9, v252, 53
	v_lshl_add_u64 v[112:113], s[10:11], 0, v[144:145]
	v_add_f32_e32 v101, v101, v103
	v_fma_f32 v101, v101, 0.5, -v99
	v_add_f32_e32 v95, v95, v97
	v_fma_f32 v95, v95, 0.5, -v91
	v_readlane_b32 s5, v252, 49
	v_readlane_b32 s6, v252, 50
	v_readlane_b32 s7, v252, 51
	v_readlane_b32 s14, v252, 58
	v_readlane_b32 s15, v252, 59
	v_readlane_b32 s16, v252, 60
	v_readlane_b32 s17, v252, 61
	v_readlane_b32 s18, v252, 62
	v_readlane_b32 s19, v252, 63
	s_waitcnt vmcnt(11)
	v_mov_b32_e32 v107, v236
	global_load_dword v248, v[80:81], off offset:-2048
	v_fmac_f32_e32 v109, v111, v107
	v_mov_b32_e32 v111, v1
	v_lshl_add_u64 v[110:111], v[142:143], 0, v[110:111]
	global_store_dword v[110:111], v109, off
	v_add_f32_e32 v109, v165, v171
	v_fma_f32 v109, v109, 0.5, -v168
	s_waitcnt vmcnt(12)
	v_mov_b32_e32 v107, v237
	global_load_dword v249, v[30:31], off offset:3072
	v_fmac_f32_e32 v168, v109, v107
	global_store_dword v[146:147], v168, off offset:1024
	v_add_f32_e32 v109, v170, v175
	v_fma_f32 v109, v109, 0.5, -v173
	s_waitcnt vmcnt(13)
	v_mov_b32_e32 v107, v238
	global_load_dword v250, v[78:79], off offset:1024
	v_fmac_f32_e32 v173, v109, v107
	global_store_dword v[146:147], v173, off offset:1280
	v_add_f32_e32 v109, v174, v179
	v_fma_f32 v109, v109, 0.5, -v176
	s_waitcnt vmcnt(14)
	v_mov_b32_e32 v107, v239
	global_load_dword v236, v[30:31], off offset:3328
	v_fmac_f32_e32 v176, v109, v107
	global_store_dword v[146:147], v176, off offset:1536
	v_add_f32_e32 v109, v178, v183
	v_fma_f32 v109, v109, 0.5, -v177
	s_waitcnt vmcnt(15)
	v_mov_b32_e32 v107, v240
	global_load_dword v237, v[78:79], off offset:1280
	v_fmac_f32_e32 v177, v109, v107
	v_mov_b32_e32 v109, v1
	v_lshl_add_u64 v[108:109], v[142:143], 0, v[108:109]
	global_store_dword v[108:109], v177, off
	v_add_f32_e32 v108, v182, v184
	v_fma_f32 v108, v108, 0.5, -v180
	s_waitcnt vmcnt(16)
	v_mov_b32_e32 v107, v241
	global_load_dword v238, v[30:31], off offset:3584
	v_fmac_f32_e32 v180, v108, v107
	v_lshl_add_u64 v[108:109], v[136:137], 0, v[16:17]
	v_lshlrev_b64 v[108:109], 2, v[108:109]
	v_lshl_add_u64 v[110:111], s[12:13], 0, v[108:109]
	global_store_dword v[110:111], v180, off offset:-2048
	v_lshl_add_u64 v[108:109], s[8:9], 0, v[108:109]
	s_waitcnt vmcnt(17)
	v_mov_b32_e32 v107, v242
	global_load_dword v239, v[78:79], off offset:1536
	v_mul_f32_e32 v107, v180, v107
	v_mul_f32_e32 v110, v107, v107
	s_nop 1
	v_mov_b32_dpp v110, v110 quad_perm:[1,0,3,2] row_mask:0xf bank_mask:0xf bound_ctrl:1
	v_fmac_f32_e32 v110, v107, v107
	s_nop 1
	v_add_f32_dpp v110, v110, v110 quad_perm:[2,3,0,1] row_mask:0xf bank_mask:0xf bound_ctrl:1
	s_nop 1
	v_add_f32_dpp v110, v110, v110 row_half_mirror row_mask:0xf bank_mask:0xf bound_ctrl:1
	s_nop 1
	v_add_f32_dpp v110, v110, v110 row_mirror row_mask:0xf bank_mask:0xf bound_ctrl:1
	ds_bpermute_b32 v111, v87, v110
	s_waitcnt lgkmcnt(0)
	v_add_f32_e32 v110, v110, v111
	ds_bpermute_b32 v111, v89, v110
	s_waitcnt lgkmcnt(0)
	v_add_f32_e32 v110, v110, v111
	v_cmp_gt_f32_e32 vcc, s4, v110
	v_mul_f32_e32 v111, 0x4f800000, v110
	s_nop 0
	v_cndmask_b32_e32 v110, v110, v111, vcc
	v_sqrt_f32_e32 v111, v110
	s_nop 0
	v_add_u32_e32 v142, -1, v111
	v_fma_f32 v143, -v142, v111, v110
	v_cmp_ge_f32_e64 s[44:45], 0, v143
	v_add_u32_e32 v143, 1, v111
	s_nop 0
	v_cndmask_b32_e64 v142, v111, v142, s[44:45]
	v_fma_f32 v111, -v143, v111, v110
	v_cmp_lt_f32_e64 s[44:45], 0, v111
	s_nop 1
	v_cndmask_b32_e64 v111, v142, v143, s[44:45]
	v_mul_f32_e32 v142, 0x37800000, v111
	v_cndmask_b32_e32 v111, v111, v142, vcc
	v_cmp_class_f32_e32 vcc, v110, v187
	s_nop 1
	v_cndmask_b32_e32 v110, v111, v110, vcc
	v_max_f32_e32 v110, 0x2b8cbccc, v110
	v_div_scale_f32 v111, s[2:3], v110, v110, v107
	v_rcp_f32_e32 v142, v111
	s_nop 0
	v_fma_f32 v143, -v111, v142, 1.0
	v_fmac_f32_e32 v142, v143, v142
	v_div_scale_f32 v143, vcc, v107, v110, v107
	v_mul_f32_e32 v144, v143, v142
	v_fma_f32 v145, -v111, v144, v143
	v_fmac_f32_e32 v144, v145, v142
	v_fma_f32 v111, -v111, v144, v143
	v_div_fmas_f32 v111, v111, v142, v144
	v_div_fixup_f32 v107, v111, v110, v107
	global_store_dword v[108:109], v107, off offset:-2048
	v_add_f32_e32 v108, v167, v172
	v_fma_f32 v108, v108, 0.5, -v166
	s_waitcnt vmcnt(18)
	v_mov_b32_e32 v107, v243
	global_load_dword v240, v[44:45], off
	v_fmac_f32_e32 v166, v108, v107
	v_lshl_add_u64 v[108:109], v[136:137], 0, v[18:19]
	v_lshlrev_b64 v[108:109], 2, v[108:109]
	v_lshl_add_u64 v[110:111], s[12:13], 0, v[108:109]
	global_store_dword v[110:111], v166, off offset:-2048
	v_lshl_add_u64 v[108:109], s[8:9], 0, v[108:109]
	s_waitcnt vmcnt(19)
	v_mov_b32_e32 v107, v244
	global_load_dword v241, v[82:83], off offset:-2048
	v_mul_f32_e32 v107, v166, v107
	v_mul_f32_e32 v110, v107, v107
	s_nop 1
	v_mov_b32_dpp v110, v110 quad_perm:[1,0,3,2] row_mask:0xf bank_mask:0xf bound_ctrl:1
	v_fmac_f32_e32 v110, v107, v107
	s_nop 1
	v_add_f32_dpp v110, v110, v110 quad_perm:[2,3,0,1] row_mask:0xf bank_mask:0xf bound_ctrl:1
	s_nop 1
	v_add_f32_dpp v110, v110, v110 row_half_mirror row_mask:0xf bank_mask:0xf bound_ctrl:1
	s_nop 1
	v_add_f32_dpp v110, v110, v110 row_mirror row_mask:0xf bank_mask:0xf bound_ctrl:1
	ds_bpermute_b32 v111, v87, v110
	s_waitcnt lgkmcnt(0)
	v_add_f32_e32 v110, v110, v111
	ds_bpermute_b32 v111, v89, v110
	s_waitcnt lgkmcnt(0)
	v_add_f32_e32 v110, v110, v111
	v_cmp_gt_f32_e32 vcc, s4, v110
	v_mul_f32_e32 v111, 0x4f800000, v110
	s_nop 0
	v_cndmask_b32_e32 v110, v110, v111, vcc
	v_sqrt_f32_e32 v111, v110
	s_nop 0
	v_add_u32_e32 v142, -1, v111
	v_fma_f32 v143, -v142, v111, v110
	v_cmp_ge_f32_e64 s[44:45], 0, v143
	v_add_u32_e32 v143, 1, v111
	s_nop 0
	v_cndmask_b32_e64 v142, v111, v142, s[44:45]
	v_fma_f32 v111, -v143, v111, v110
	v_cmp_lt_f32_e64 s[44:45], 0, v111
	s_nop 1
	v_cndmask_b32_e64 v111, v142, v143, s[44:45]
	v_mul_f32_e32 v142, 0x37800000, v111
	v_cndmask_b32_e32 v111, v111, v142, vcc
	v_cmp_class_f32_e32 vcc, v110, v187
	s_nop 1
	v_cndmask_b32_e32 v110, v111, v110, vcc
	v_max_f32_e32 v110, 0x2b8cbccc, v110
	v_div_scale_f32 v111, s[2:3], v110, v110, v107
	v_rcp_f32_e32 v142, v111
	s_nop 0
	v_fma_f32 v143, -v111, v142, 1.0
	v_fmac_f32_e32 v142, v143, v142
	v_div_scale_f32 v143, vcc, v107, v110, v107
	v_mul_f32_e32 v144, v143, v142
	v_fma_f32 v145, -v111, v144, v143
	v_fmac_f32_e32 v144, v145, v142
	v_fma_f32 v111, -v111, v144, v143
	v_div_fmas_f32 v111, v111, v142, v144
	v_div_fixup_f32 v107, v111, v110, v107
	global_store_dword v[108:109], v107, off offset:-2048
	v_add_f32_e32 v108, v163, v164
	v_fma_f32 v108, v108, 0.5, -v162
	s_waitcnt vmcnt(20)
	v_mov_b32_e32 v107, v245
	global_load_dword v242, v[46:47], off
	v_fmac_f32_e32 v162, v108, v107
	v_lshl_add_u64 v[108:109], v[136:137], 0, v[20:21]
	v_lshlrev_b64 v[108:109], 2, v[108:109]
	v_lshl_add_u64 v[110:111], s[12:13], 0, v[108:109]
	global_store_dword v[110:111], v162, off offset:-2048
	v_lshl_add_u64 v[108:109], s[8:9], 0, v[108:109]
	s_waitcnt vmcnt(21)
	v_mov_b32_e32 v107, v246
	global_load_dword v243, v[48:49], off
	v_mul_f32_e32 v107, v162, v107
	v_mul_f32_e32 v110, v107, v107
	s_nop 1
	v_mov_b32_dpp v110, v110 quad_perm:[1,0,3,2] row_mask:0xf bank_mask:0xf bound_ctrl:1
	v_fmac_f32_e32 v110, v107, v107
	s_nop 1
	v_add_f32_dpp v110, v110, v110 quad_perm:[2,3,0,1] row_mask:0xf bank_mask:0xf bound_ctrl:1
	s_nop 1
	v_add_f32_dpp v110, v110, v110 row_half_mirror row_mask:0xf bank_mask:0xf bound_ctrl:1
	s_nop 1
	v_add_f32_dpp v110, v110, v110 row_mirror row_mask:0xf bank_mask:0xf bound_ctrl:1
	ds_bpermute_b32 v111, v87, v110
	s_waitcnt lgkmcnt(0)
	v_add_f32_e32 v110, v110, v111
	ds_bpermute_b32 v111, v89, v110
	s_waitcnt lgkmcnt(0)
	v_add_f32_e32 v110, v110, v111
	v_cmp_gt_f32_e32 vcc, s4, v110
	v_mul_f32_e32 v111, 0x4f800000, v110
	s_nop 0
	v_cndmask_b32_e32 v110, v110, v111, vcc
	v_sqrt_f32_e32 v111, v110
	s_nop 0
	v_add_u32_e32 v142, -1, v111
	v_fma_f32 v143, -v142, v111, v110
	v_cmp_ge_f32_e64 s[44:45], 0, v143
	v_add_u32_e32 v143, 1, v111
	s_nop 0
	v_cndmask_b32_e64 v142, v111, v142, s[44:45]
	v_fma_f32 v111, -v143, v111, v110
	v_cmp_lt_f32_e64 s[44:45], 0, v111
	s_nop 1
	v_cndmask_b32_e64 v111, v142, v143, s[44:45]
	v_mul_f32_e32 v142, 0x37800000, v111
	v_cndmask_b32_e32 v111, v111, v142, vcc
	v_cmp_class_f32_e32 vcc, v110, v187
	s_nop 1
	v_cndmask_b32_e32 v110, v111, v110, vcc
	v_max_f32_e32 v110, 0x2b8cbccc, v110
	v_div_scale_f32 v111, s[2:3], v110, v110, v107
	v_rcp_f32_e32 v142, v111
	s_nop 0
	v_fma_f32 v143, -v111, v142, 1.0
	v_fmac_f32_e32 v142, v143, v142
	v_div_scale_f32 v143, vcc, v107, v110, v107
	v_mul_f32_e32 v144, v143, v142
	v_fma_f32 v145, -v111, v144, v143
	v_fmac_f32_e32 v144, v145, v142
	v_fma_f32 v111, -v111, v144, v143
	v_div_fmas_f32 v111, v111, v142, v144
	v_div_fixup_f32 v107, v111, v110, v107
	global_store_dword v[108:109], v107, off offset:-2048
	v_add_f32_e32 v108, v160, v161
	v_fma_f32 v108, v108, 0.5, -v159
	s_waitcnt vmcnt(22)
	v_mov_b32_e32 v107, v247
	global_load_dword v244, v[50:51], off
	v_fmac_f32_e32 v159, v108, v107
	v_lshl_add_u64 v[108:109], v[136:137], 0, v[22:23]
	v_lshlrev_b64 v[108:109], 2, v[108:109]
	v_lshl_add_u64 v[110:111], s[12:13], 0, v[108:109]
	global_store_dword v[110:111], v159, off offset:-2048
	v_lshl_add_u64 v[108:109], s[8:9], 0, v[108:109]
	s_waitcnt vmcnt(23)
	v_mov_b32_e32 v107, v248
	global_load_dword v245, v[52:53], off
	v_mul_f32_e32 v107, v159, v107
	v_mul_f32_e32 v110, v107, v107
	s_nop 1
	v_mov_b32_dpp v110, v110 quad_perm:[1,0,3,2] row_mask:0xf bank_mask:0xf bound_ctrl:1
	v_fmac_f32_e32 v110, v107, v107
	s_nop 1
	v_add_f32_dpp v110, v110, v110 quad_perm:[2,3,0,1] row_mask:0xf bank_mask:0xf bound_ctrl:1
	s_nop 1
	v_add_f32_dpp v110, v110, v110 row_half_mirror row_mask:0xf bank_mask:0xf bound_ctrl:1
	s_nop 1
	v_add_f32_dpp v110, v110, v110 row_mirror row_mask:0xf bank_mask:0xf bound_ctrl:1
	ds_bpermute_b32 v111, v87, v110
	s_waitcnt lgkmcnt(0)
	v_add_f32_e32 v110, v110, v111
	ds_bpermute_b32 v111, v89, v110
	s_waitcnt lgkmcnt(0)
	v_add_f32_e32 v110, v110, v111
	v_cmp_gt_f32_e32 vcc, s4, v110
	v_mul_f32_e32 v111, 0x4f800000, v110
	s_nop 0
	v_cndmask_b32_e32 v110, v110, v111, vcc
	v_sqrt_f32_e32 v111, v110
	s_nop 0
	v_add_u32_e32 v142, -1, v111
	v_fma_f32 v143, -v142, v111, v110
	v_cmp_ge_f32_e64 s[44:45], 0, v143
	v_add_u32_e32 v143, 1, v111
	s_nop 0
	v_cndmask_b32_e64 v142, v111, v142, s[44:45]
	v_fma_f32 v111, -v143, v111, v110
	v_cmp_lt_f32_e64 s[44:45], 0, v111
	s_nop 1
	v_cndmask_b32_e64 v111, v142, v143, s[44:45]
	v_mul_f32_e32 v142, 0x37800000, v111
	v_cndmask_b32_e32 v111, v111, v142, vcc
	v_cmp_class_f32_e32 vcc, v110, v187
	s_nop 1
	v_cndmask_b32_e32 v110, v111, v110, vcc
	v_max_f32_e32 v110, 0x2b8cbccc, v110
	v_div_scale_f32 v111, s[2:3], v110, v110, v107
	v_rcp_f32_e32 v142, v111
	s_nop 0
	v_fma_f32 v143, -v111, v142, 1.0
	v_fmac_f32_e32 v142, v143, v142
	v_div_scale_f32 v143, vcc, v107, v110, v107
	v_mul_f32_e32 v144, v143, v142
	v_fma_f32 v145, -v111, v144, v143
	v_fmac_f32_e32 v144, v145, v142
	v_fma_f32 v111, -v111, v144, v143
	v_div_fmas_f32 v111, v111, v142, v144
	v_div_fixup_f32 v107, v111, v110, v107
	global_store_dword v[108:109], v107, off offset:-2048
	v_add_f32_e32 v108, v156, v157
	v_fma_f32 v108, v108, 0.5, -v105
	s_waitcnt vmcnt(23)
	v_mov_b32_e32 v107, v249
	global_load_dword v246, v[54:55], off
	v_fmac_f32_e32 v105, v108, v107
	v_lshl_add_u64 v[108:109], v[136:137], 0, v[24:25]
	v_lshlrev_b64 v[108:109], 2, v[108:109]
	v_lshl_add_u64 v[110:111], s[12:13], 0, v[108:109]
	global_store_dword v[110:111], v105, off offset:-2048
	v_lshl_add_u64 v[108:109], s[8:9], 0, v[108:109]
	s_waitcnt vmcnt(23)
	v_mov_b32_e32 v107, v250
	global_load_dword v247, v[56:57], off
	v_mul_f32_e32 v105, v105, v107
	v_mul_f32_e32 v107, v105, v105
	s_nop 1
	v_mov_b32_dpp v107, v107 quad_perm:[1,0,3,2] row_mask:0xf bank_mask:0xf bound_ctrl:1
	v_fmac_f32_e32 v107, v105, v105
	s_nop 1
	v_add_f32_dpp v107, v107, v107 quad_perm:[2,3,0,1] row_mask:0xf bank_mask:0xf bound_ctrl:1
	s_nop 1
	v_add_f32_dpp v107, v107, v107 row_half_mirror row_mask:0xf bank_mask:0xf bound_ctrl:1
	s_nop 1
	v_add_f32_dpp v107, v107, v107 row_mirror row_mask:0xf bank_mask:0xf bound_ctrl:1
	ds_bpermute_b32 v110, v87, v107
	s_waitcnt lgkmcnt(0)
	v_add_f32_e32 v107, v107, v110
	ds_bpermute_b32 v110, v89, v107
	s_waitcnt lgkmcnt(0)
	v_add_f32_e32 v107, v107, v110
	v_cmp_gt_f32_e32 vcc, s4, v107
	v_mul_f32_e32 v110, 0x4f800000, v107
	s_nop 0
	v_cndmask_b32_e32 v107, v107, v110, vcc
	v_sqrt_f32_e32 v110, v107
	s_nop 0
	v_add_u32_e32 v111, -1, v110
	v_fma_f32 v142, -v111, v110, v107
	v_cmp_ge_f32_e64 s[44:45], 0, v142
	v_add_u32_e32 v142, 1, v110
	s_nop 0
	v_cndmask_b32_e64 v111, v110, v111, s[44:45]
	v_fma_f32 v110, -v142, v110, v107
	v_cmp_lt_f32_e64 s[44:45], 0, v110
	s_nop 1
	v_cndmask_b32_e64 v110, v111, v142, s[44:45]
	v_mul_f32_e32 v111, 0x37800000, v110
	v_cndmask_b32_e32 v110, v110, v111, vcc
	v_cmp_class_f32_e32 vcc, v107, v187
	s_nop 1
	v_cndmask_b32_e32 v107, v110, v107, vcc
	v_max_f32_e32 v107, 0x2b8cbccc, v107
	v_div_scale_f32 v110, s[2:3], v107, v107, v105
	v_rcp_f32_e32 v111, v110
	s_nop 0
	v_fma_f32 v142, -v110, v111, 1.0
	v_fmac_f32_e32 v111, v142, v111
	v_div_scale_f32 v142, vcc, v105, v107, v105
	v_mul_f32_e32 v143, v142, v111
	v_fma_f32 v144, -v110, v143, v142
	v_fmac_f32_e32 v143, v144, v111
	v_fma_f32 v110, -v110, v143, v142
	v_div_fmas_f32 v110, v110, v111, v143
	v_div_fixup_f32 v105, v110, v107, v105
	global_store_dword v[108:109], v105, off offset:-2048
	v_lshl_add_u64 v[108:109], v[136:137], 0, v[26:27]
	v_lshlrev_b64 v[108:109], 2, v[108:109]
	v_lshl_add_u64 v[110:111], s[12:13], 0, v[108:109]
	v_lshl_add_u64 v[108:109], s[8:9], 0, v[108:109]
	s_waitcnt vmcnt(23)
	v_mov_b32_e32 v105, v236
	global_load_dword v248, v[58:59], off
	v_fmac_f32_e32 v99, v101, v105
	global_store_dword v[110:111], v99, off offset:-2048
	s_waitcnt vmcnt(23)
	v_mov_b32_e32 v101, v237
	global_load_dword v249, v[60:61], off
	v_mul_f32_e32 v99, v99, v101
	v_mul_f32_e32 v101, v99, v99
	s_nop 1
	v_mov_b32_dpp v101, v101 quad_perm:[1,0,3,2] row_mask:0xf bank_mask:0xf bound_ctrl:1
	v_fmac_f32_e32 v101, v99, v99
	s_nop 1
	v_add_f32_dpp v101, v101, v101 quad_perm:[2,3,0,1] row_mask:0xf bank_mask:0xf bound_ctrl:1
	s_nop 1
	v_add_f32_dpp v101, v101, v101 row_half_mirror row_mask:0xf bank_mask:0xf bound_ctrl:1
	s_nop 1
	v_add_f32_dpp v101, v101, v101 row_mirror row_mask:0xf bank_mask:0xf bound_ctrl:1
	ds_bpermute_b32 v103, v87, v101
	s_waitcnt lgkmcnt(0)
	v_add_f32_e32 v101, v101, v103
	ds_bpermute_b32 v103, v89, v101
	s_waitcnt lgkmcnt(0)
	v_add_f32_e32 v101, v101, v103
	v_cmp_gt_f32_e32 vcc, s4, v101
	v_mul_f32_e32 v103, 0x4f800000, v101
	s_nop 0
	v_cndmask_b32_e32 v101, v101, v103, vcc
	v_sqrt_f32_e32 v103, v101
	s_nop 0
	v_add_u32_e32 v105, -1, v103
	v_fma_f32 v107, -v105, v103, v101
	v_cmp_ge_f32_e64 s[44:45], 0, v107
	v_add_u32_e32 v107, 1, v103
	s_nop 0
	v_cndmask_b32_e64 v105, v103, v105, s[44:45]
	v_fma_f32 v103, -v107, v103, v101
	v_cmp_lt_f32_e64 s[44:45], 0, v103
	s_nop 1
	v_cndmask_b32_e64 v103, v105, v107, s[44:45]
	v_mul_f32_e32 v105, 0x37800000, v103
	v_cndmask_b32_e32 v103, v103, v105, vcc
	v_cmp_class_f32_e32 vcc, v101, v187
	s_nop 1
	v_cndmask_b32_e32 v101, v103, v101, vcc
	v_max_f32_e32 v101, 0x2b8cbccc, v101
	v_div_scale_f32 v103, s[2:3], v101, v101, v99
	v_rcp_f32_e32 v105, v103
	s_nop 0
	v_fma_f32 v107, -v103, v105, 1.0
	v_fmac_f32_e32 v105, v107, v105
	v_div_scale_f32 v107, vcc, v99, v101, v99
	v_mul_f32_e32 v110, v107, v105
	v_fma_f32 v111, -v103, v110, v107
	v_fmac_f32_e32 v110, v111, v105
	v_fma_f32 v103, -v103, v110, v107
	v_div_fmas_f32 v103, v103, v105, v110
	v_div_fixup_f32 v99, v103, v101, v99
	global_store_dword v[108:109], v99, off offset:-2048
	v_lshl_add_u64 v[108:109], v[136:137], 0, v[28:29]
	v_lshlrev_b64 v[108:109], 2, v[108:109]
	v_lshl_add_u64 v[110:111], s[12:13], 0, v[108:109]
	v_lshl_add_u64 v[108:109], s[8:9], 0, v[108:109]
	s_waitcnt vmcnt(23)
	v_mov_b32_e32 v99, v238
	global_load_dword v250, v[62:63], off
	v_fmac_f32_e32 v91, v95, v99
	global_store_dword v[110:111], v91, off offset:-2048
	s_waitcnt vmcnt(23)
	v_mov_b32_e32 v95, v239
	global_load_dword v236, v[64:65], off
	v_mul_f32_e32 v91, v91, v95
	v_mul_f32_e32 v95, v91, v91
	s_nop 1
	v_mov_b32_dpp v95, v95 quad_perm:[1,0,3,2] row_mask:0xf bank_mask:0xf bound_ctrl:1
	v_fmac_f32_e32 v95, v91, v91
	s_nop 1
	v_add_f32_dpp v95, v95, v95 quad_perm:[2,3,0,1] row_mask:0xf bank_mask:0xf bound_ctrl:1
	s_nop 1
	v_add_f32_dpp v95, v95, v95 row_half_mirror row_mask:0xf bank_mask:0xf bound_ctrl:1
	s_nop 1
	v_add_f32_dpp v95, v95, v95 row_mirror row_mask:0xf bank_mask:0xf bound_ctrl:1
	ds_bpermute_b32 v97, v87, v95
	s_waitcnt lgkmcnt(0)
	v_add_f32_e32 v95, v95, v97
	ds_bpermute_b32 v97, v89, v95
	s_waitcnt lgkmcnt(0)
	v_add_f32_e32 v95, v95, v97
	v_cmp_gt_f32_e32 vcc, s4, v95
	v_mul_f32_e32 v97, 0x4f800000, v95
	s_nop 0
	v_cndmask_b32_e32 v95, v95, v97, vcc
	v_sqrt_f32_e32 v97, v95
	s_nop 0
	v_add_u32_e32 v99, -1, v97
	v_fma_f32 v101, -v99, v97, v95
	v_cmp_ge_f32_e64 s[44:45], 0, v101
	v_add_u32_e32 v101, 1, v97
	s_nop 0
	v_cndmask_b32_e64 v99, v97, v99, s[44:45]
	v_fma_f32 v97, -v101, v97, v95
	v_cmp_lt_f32_e64 s[44:45], 0, v97
	s_nop 1
	v_cndmask_b32_e64 v97, v99, v101, s[44:45]
	v_mul_f32_e32 v99, 0x37800000, v97
	v_cndmask_b32_e32 v97, v97, v99, vcc
	v_cmp_class_f32_e32 vcc, v95, v187
	s_nop 1
	v_cndmask_b32_e32 v95, v97, v95, vcc
	v_max_f32_e32 v95, 0x2b8cbccc, v95
	v_div_scale_f32 v97, s[2:3], v95, v95, v91
	v_rcp_f32_e32 v99, v97
	s_nop 0
	v_fma_f32 v101, -v97, v99, 1.0
	v_fmac_f32_e32 v99, v101, v99
	v_div_scale_f32 v101, vcc, v91, v95, v91
	v_mul_f32_e32 v103, v101, v99
	v_fma_f32 v105, -v97, v103, v101
	v_fmac_f32_e32 v103, v105, v99
	v_fma_f32 v97, -v97, v103, v101
	v_div_fmas_f32 v97, v97, v99, v103
	v_div_fixup_f32 v91, v97, v95, v91
	global_store_dword v[108:109], v91, off offset:-2048
	v_add_f32_e32 v95, v231, v230
	v_lshl_add_u64 v[108:109], v[136:137], 0, v[32:33]
	v_fma_f32 v95, v95, 0.5, -v224
	v_lshlrev_b64 v[108:109], 2, v[108:109]
	v_lshl_add_u64 v[110:111], s[12:13], 0, v[108:109]
	v_lshl_add_u64 v[108:109], s[8:9], 0, v[108:109]
	v_mov_b32_e32 v103, v1
	v_mov_b32_e32 v105, v1
	s_waitcnt vmcnt(23)
	v_mov_b32_e32 v91, v240
	global_load_dword v237, v[66:67], off
	v_fmac_f32_e32 v224, v95, v91
	global_store_dword v[110:111], v224, off offset:-2048
	s_waitcnt vmcnt(23)
	v_mov_b32_e32 v91, v241
	global_load_dword v238, v[68:69], off
	v_mul_f32_e32 v91, v224, v91
	v_mul_f32_e32 v95, v91, v91
	s_nop 1
	v_mov_b32_dpp v95, v95 quad_perm:[1,0,3,2] row_mask:0xf bank_mask:0xf bound_ctrl:1
	v_fmac_f32_e32 v95, v91, v91
	s_nop 1
	v_add_f32_dpp v95, v95, v95 quad_perm:[2,3,0,1] row_mask:0xf bank_mask:0xf bound_ctrl:1
	s_nop 1
	v_add_f32_dpp v95, v95, v95 row_half_mirror row_mask:0xf bank_mask:0xf bound_ctrl:1
	s_nop 1
	v_add_f32_dpp v95, v95, v95 row_mirror row_mask:0xf bank_mask:0xf bound_ctrl:1
	ds_bpermute_b32 v87, v87, v95
	s_waitcnt lgkmcnt(0)
	v_add_f32_e32 v87, v95, v87
	ds_bpermute_b32 v89, v89, v87
	s_waitcnt lgkmcnt(0)
	v_add_f32_e32 v87, v87, v89
	v_cmp_gt_f32_e32 vcc, s4, v87
	v_mul_f32_e32 v89, 0x4f800000, v87
	s_nop 0
	v_cndmask_b32_e32 v87, v87, v89, vcc
	v_sqrt_f32_e32 v89, v87
	s_nop 0
	v_add_u32_e32 v95, -1, v89
	v_fma_f32 v97, -v95, v89, v87
	v_cmp_ge_f32_e64 s[44:45], 0, v97
	v_add_u32_e32 v97, 1, v89
	s_nop 0
	v_cndmask_b32_e64 v95, v89, v95, s[44:45]
	v_fma_f32 v89, -v97, v89, v87
	v_cmp_lt_f32_e64 s[44:45], 0, v89
	s_nop 1
	v_cndmask_b32_e64 v89, v95, v97, s[44:45]
	v_mul_f32_e32 v95, 0x37800000, v89
	v_cndmask_b32_e32 v89, v89, v95, vcc
	v_cmp_class_f32_e32 vcc, v87, v187
	s_nop 1
	v_cndmask_b32_e32 v87, v89, v87, vcc
	v_max_f32_e32 v87, 0x2b8cbccc, v87
	v_div_scale_f32 v89, s[2:3], v87, v87, v91
	v_rcp_f32_e32 v95, v89
	s_nop 0
	v_fma_f32 v97, -v89, v95, 1.0
	v_fmac_f32_e32 v95, v97, v95
	v_div_scale_f32 v97, vcc, v91, v87, v91
	v_mul_f32_e32 v99, v97, v95
	v_fma_f32 v101, -v89, v99, v97
	v_fmac_f32_e32 v99, v101, v95
	v_fma_f32 v89, -v89, v99, v97
	v_div_fmas_f32 v89, v89, v95, v99
	v_div_fixup_f32 v87, v89, v87, v91
	global_store_dword v[108:109], v87, off offset:-2048
	v_add_f32_e32 v89, v185, v204
	v_fma_f32 v89, v89, 0.5, -v152
	v_mov_b32_e32 v95, v1
	v_lshl_add_u64 v[108:109], v[112:113], 0, v[94:95]
	v_mov_b32_e32 v97, v1
	v_mov_b32_e32 v99, v1
	v_mov_b32_e32 v101, v1
	s_waitcnt vmcnt(23)
	v_mov_b32_e32 v87, v242
	global_load_dword v239, v[70:71], off
	v_fmac_f32_e32 v152, v89, v87
	global_store_dword v[108:109], v152, off offset:-4096
	v_add_f32_e32 v89, v206, v207
	v_fma_f32 v89, v89, 0.5, -v155
	v_lshl_add_u64 v[108:109], v[112:113], 0, v[96:97]
	s_waitcnt vmcnt(23)
	v_mov_b32_e32 v87, v243
	global_load_dword v240, v[72:73], off
	v_fmac_f32_e32 v155, v89, v87
	global_store_dword v[108:109], v155, off offset:-4096
	v_add_f32_e32 v89, v209, v211
	v_fma_f32 v89, v89, 0.5, -v205
	v_lshl_add_u64 v[108:109], v[112:113], 0, v[98:99]
	s_waitcnt vmcnt(23)
	v_mov_b32_e32 v87, v244
	v_fmac_f32_e32 v205, v89, v87
	global_store_dword v[108:109], v205, off offset:-4096
	v_add_f32_e32 v89, v215, v214
	v_fma_f32 v89, v89, 0.5, -v208
	v_lshl_add_u64 v[108:109], v[112:113], 0, v[0:1]
	s_waitcnt vmcnt(22)
	v_mov_b32_e32 v87, v245
	v_fmac_f32_e32 v208, v89, v87
	global_store_dword v[108:109], v208, off offset:-4096
	v_add_f32_e32 v87, v218, v219
	v_fma_f32 v87, v87, 0.5, -v216
	v_lshl_add_u64 v[108:109], v[112:113], 0, v[100:101]
	s_waitcnt vmcnt(21)
	v_mov_b32_e32 v0, v246
	v_fmac_f32_e32 v216, v87, v0
	global_store_dword v[108:109], v216, off offset:-4096
	v_add_f32_e32 v87, v223, v227
	v_fma_f32 v87, v87, 0.5, -v217
	v_lshl_add_u64 v[108:109], v[112:113], 0, v[102:103]
	s_waitcnt vmcnt(20)
	v_mov_b32_e32 v0, v247
	v_fmac_f32_e32 v217, v87, v0
	global_store_dword v[108:109], v217, off offset:-4096
	v_add_f32_e32 v87, v228, v229
	v_fma_f32 v87, v87, 0.5, -v221
	v_lshl_add_u64 v[108:109], v[112:113], 0, v[104:105]
	s_waitcnt vmcnt(19)
	v_mov_b32_e32 v0, v248
	v_fmac_f32_e32 v221, v87, v0
	global_store_dword v[108:109], v221, off offset:-4096
	v_add_f32_e32 v87, v232, v141
	v_fma_f32 v87, v87, 0.5, -v226
	v_mov_b32_e32 v141, v1
	v_lshl_add_u64 v[108:109], v[112:113], 0, v[140:141]
	s_waitcnt vmcnt(18)
	v_mov_b32_e32 v0, v249
	v_fmac_f32_e32 v226, v87, v0
	global_store_dword v[108:109], v226, off offset:-4096
	v_add_f32_e32 v87, v234, v235
	v_fma_f32 v87, v87, 0.5, -v233
	s_waitcnt vmcnt(17)
	v_mov_b32_e32 v0, v250
	v_fmac_f32_e32 v233, v87, v0
	v_mul_f32_e32 v0, 0xbfb8aa3b, v233
	v_exp_f32_e32 v0, v0
	s_nop 0
	v_add_f32_e32 v0, 1.0, v0
	v_div_scale_f32 v87, s[2:3], v0, v0, 1.0
	v_rcp_f32_e32 v89, v87
	s_movk_i32 s2, 0x300
	v_mad_i64_i32 v[106:107], s[2:3], v106, s2, v[84:85]
	v_fma_f32 v91, -v87, v89, 1.0
	v_fmac_f32_e32 v89, v91, v89
	v_div_scale_f32 v91, vcc, 1.0, v0, 1.0
	v_mul_f32_e32 v95, v91, v89
	v_fma_f32 v97, -v87, v95, v91
	v_fmac_f32_e32 v95, v97, v89
	v_fma_f32 v87, -v87, v95, v91
	v_div_fmas_f32 v87, v87, v89, v95
	v_div_fixup_f32 v0, v87, v0, 1.0
	v_cvt_pk_bf16_f32 v0, v0, s0
	global_store_short v[106:107], v0, off offset:512
	v_add_f32_e32 v87, v222, v225
	v_fma_f32 v87, v87, 0.5, -v220
	s_waitcnt vmcnt(16)
	v_mov_b32_e32 v0, v236
	v_fmac_f32_e32 v220, v87, v0
	v_mul_f32_e32 v0, 0xbfb8aa3b, v220
	v_exp_f32_e32 v0, v0
	s_nop 0
	v_add_f32_e32 v0, 1.0, v0
	v_div_scale_f32 v87, s[2:3], v0, v0, 1.0
	v_rcp_f32_e32 v89, v87
	s_nop 0
	v_fma_f32 v91, -v87, v89, 1.0
	v_fmac_f32_e32 v89, v91, v89
	v_div_scale_f32 v91, vcc, 1.0, v0, 1.0
	v_mul_f32_e32 v95, v91, v89
	v_fma_f32 v97, -v87, v95, v91
	v_fmac_f32_e32 v95, v97, v89
	v_fma_f32 v87, -v87, v95, v91
	v_div_fmas_f32 v87, v87, v89, v95
	v_div_fixup_f32 v0, v87, v0, 1.0
	v_cvt_pk_bf16_f32 v0, v0, s0
	global_store_short v[106:107], v0, off offset:640
	v_add_f32_e32 v87, v212, v213
	v_fma_f32 v87, v87, 0.5, -v210
	s_waitcnt vmcnt(15)
	v_mov_b32_e32 v0, v237
	v_fmac_f32_e32 v210, v87, v0
	v_add_f32_e32 v0, v210, v210
	v_mul_f32_e32 v0, 0x3fb8aa3b, v0
	v_exp_f32_e32 v0, v0
	s_nop 0
	v_add_f32_e32 v0, 1.0, v0
	v_div_scale_f32 v87, s[2:3], v0, v0, 2.0
	v_rcp_f32_e32 v89, v87
	s_nop 0
	v_fma_f32 v91, -v87, v89, 1.0
	v_fmac_f32_e32 v89, v91, v89
	v_div_scale_f32 v91, vcc, 2.0, v0, 2.0
	v_mul_f32_e32 v95, v91, v89
	v_fma_f32 v97, -v87, v95, v91
	v_fmac_f32_e32 v95, v97, v89
	v_fma_f32 v87, -v87, v95, v91
	v_div_fmas_f32 v87, v87, v89, v95
	v_div_fixup_f32 v0, v87, v0, 2.0
	v_sub_f32_e32 v0, 1.0, v0
	v_cvt_pk_bf16_f32 v0, v0, s0
	global_store_short v[106:107], v0, off
	v_add_f32_e32 v87, v154, v153
	v_fma_f32 v87, v87, 0.5, -v151
	s_waitcnt vmcnt(14)
	v_mov_b32_e32 v0, v238
	v_fmac_f32_e32 v151, v87, v0
	v_add_f32_e32 v0, v151, v151
	v_mul_f32_e32 v0, 0x3fb8aa3b, v0
	v_exp_f32_e32 v0, v0
	s_nop 0
	v_add_f32_e32 v0, 1.0, v0
	v_div_scale_f32 v87, s[2:3], v0, v0, 2.0
	v_rcp_f32_e32 v89, v87
	s_nop 0
	v_fma_f32 v91, -v87, v89, 1.0
	v_fmac_f32_e32 v89, v91, v89
	v_div_scale_f32 v91, vcc, 2.0, v0, 2.0
	v_mul_f32_e32 v95, v91, v89
	v_fma_f32 v97, -v87, v95, v91
	v_fmac_f32_e32 v95, v97, v89
	v_fma_f32 v87, -v87, v95, v91
	v_div_fmas_f32 v87, v87, v89, v95
	v_div_fixup_f32 v0, v87, v0, 2.0
	v_sub_f32_e32 v0, 1.0, v0
	v_cvt_pk_bf16_f32 v0, v0, s0
	global_store_short v[106:107], v0, off offset:128
	v_add_f32_e32 v87, v148, v150
	v_fma_f32 v87, v87, 0.5, -v139
	s_waitcnt vmcnt(13)
	v_mov_b32_e32 v0, v239
	v_fmac_f32_e32 v139, v87, v0
	v_cvt_pk_bf16_f32 v0, v139, s0
	global_store_short v[106:107], v0, off offset:256
	v_add_f32_e32 v87, v138, v149
	v_fma_f32 v87, v87, 0.5, -v93
	s_waitcnt vmcnt(12)
	v_mov_b32_e32 v0, v240
	v_fmac_f32_e32 v93, v87, v0
	v_cvt_pk_bf16_f32 v0, v93, s0
	global_store_short v[106:107], v0, off offset:384
